# conversion loops of the first block: s_sleep 8 pacing after each row pair
# speedup vs baseline: 1.0087x; 1.0034x over previous
; template <int MODE> __device__ __forceinline__ void transpose_item(const float* W, int K, int N, bf16_t* WT, LAS float* scr, int item, int lane) {
;     const int nblk = N / 32, kb = item / nblk, nb = item % nblk, k0 = 64 * kb, n0 = 32 * nb;
; #pragma unroll 8
;     for (int i = 0; i < 32; ++i) { const int kk = 2 * i + (lane >> 5); scr[kk * 33 + (lane & 31)] = W[(size_t)(k0 + kk) * N + n0 + (lane & 31)]; }
.LBB0_152:
	s_lshl_b32 s16, s10, 1
	s_lshl_b32 s14, s7, 1
	v_or_b32_e32 v18, s16, v10
	v_or_b32_e32 v16, s14, v5
	v_ashrrev_i32_e32 v19, 31, v18
	v_ashrrev_i32_e32 v17, 31, v16
	v_lshlrev_b64 v[18:19], 12, v[18:19]
	v_lshlrev_b64 v[16:17], 12, v[16:17]
	v_lshl_add_u64 v[18:19], v[8:9], 0, v[18:19]
	v_lshl_add_u64 v[16:17], v[8:9], 0, v[16:17]
	global_load_dword v21, v[18:19], off
	global_load_dword v22, v[16:17], off
	v_or_b32_e32 v7, s14, v3
	v_or_b32_e32 v20, s16, v2
	v_mad_u64_u32 v[16:17], s[34:35], v20, s83, v[4:5]
	v_mad_u64_u32 v[18:19], s[34:35], v7, s83, v[4:5]
	s_add_i32 s18, s16, 4
	s_add_i32 s17, s14, 4
	v_or_b32_e32 v7, s17, v3
	v_or_b32_e32 v20, s18, v2
	s_add_i32 s10, s10, 16
	s_add_i32 s7, s7, 16
	s_add_i32 s11, s11, -16
	s_waitcnt vmcnt(0)
	ds_write_b32 v16, v21
	s_sleep 8
	ds_write_b32 v18, v22
	v_or_b32_e32 v18, s18, v10
	v_or_b32_e32 v16, s17, v5
	v_ashrrev_i32_e32 v19, 31, v18
	v_ashrrev_i32_e32 v17, 31, v16
	v_lshlrev_b64 v[18:19], 12, v[18:19]
	v_lshlrev_b64 v[16:17], 12, v[16:17]
	v_lshl_add_u64 v[18:19], v[8:9], 0, v[18:19]
	v_lshl_add_u64 v[16:17], v[8:9], 0, v[16:17]
	global_load_dword v21, v[18:19], off
	global_load_dword v22, v[16:17], off
	v_mad_u64_u32 v[16:17], s[34:35], v20, s83, v[4:5]
	v_mad_u64_u32 v[18:19], s[34:35], v7, s83, v[4:5]
	s_add_i32 s18, s16, 8
	s_add_i32 s17, s14, 8
	v_or_b32_e32 v7, s17, v3
	v_or_b32_e32 v20, s18, v2
	s_waitcnt vmcnt(1)
	ds_write_b32 v16, v21
	s_waitcnt vmcnt(0)
	ds_write_b32 v18, v22
	s_sleep 8
	v_or_b32_e32 v18, s18, v10
	v_or_b32_e32 v16, s17, v5
	v_ashrrev_i32_e32 v19, 31, v18
	v_ashrrev_i32_e32 v17, 31, v16
	v_lshlrev_b64 v[18:19], 12, v[18:19]
	v_lshlrev_b64 v[16:17], 12, v[16:17]
	v_lshl_add_u64 v[18:19], v[8:9], 0, v[18:19]
	v_lshl_add_u64 v[16:17], v[8:9], 0, v[16:17]
	global_load_dword v21, v[18:19], off
	global_load_dword v22, v[16:17], off
	v_mad_u64_u32 v[16:17], s[34:35], v20, s83, v[4:5]
	v_mad_u64_u32 v[18:19], s[34:35], v7, s83, v[4:5]
	s_add_i32 s18, s16, 12
	s_add_i32 s17, s14, 12
	v_or_b32_e32 v7, s17, v3
	v_or_b32_e32 v20, s18, v2
	s_waitcnt vmcnt(1)
	ds_write_b32 v16, v21
	s_waitcnt vmcnt(0)
	ds_write_b32 v18, v22
	s_sleep 8
	v_or_b32_e32 v18, s18, v10
	v_or_b32_e32 v16, s17, v5
	v_ashrrev_i32_e32 v19, 31, v18
	v_ashrrev_i32_e32 v17, 31, v16
	v_lshlrev_b64 v[18:19], 12, v[18:19]
	v_lshlrev_b64 v[16:17], 12, v[16:17]
	v_lshl_add_u64 v[18:19], v[8:9], 0, v[18:19]
	v_lshl_add_u64 v[16:17], v[8:9], 0, v[16:17]
	global_load_dword v21, v[18:19], off
	global_load_dword v22, v[16:17], off
	v_mad_u64_u32 v[16:17], s[34:35], v20, s83, v[4:5]
	v_mad_u64_u32 v[18:19], s[34:35], v7, s83, v[4:5]
	s_add_i32 s18, s16, 16
	s_add_i32 s17, s14, 16
	v_or_b32_e32 v7, s17, v3
	v_or_b32_e32 v20, s18, v2
	s_waitcnt vmcnt(1)
	ds_write_b32 v16, v21
	s_waitcnt vmcnt(0)
	ds_write_b32 v18, v22
	s_sleep 8
	v_or_b32_e32 v18, s18, v10
	v_or_b32_e32 v16, s17, v5
	v_ashrrev_i32_e32 v19, 31, v18
	v_ashrrev_i32_e32 v17, 31, v16
	v_lshlrev_b64 v[18:19], 12, v[18:19]
	v_lshlrev_b64 v[16:17], 12, v[16:17]
	v_lshl_add_u64 v[18:19], v[8:9], 0, v[18:19]
	v_lshl_add_u64 v[16:17], v[8:9], 0, v[16:17]
	global_load_dword v21, v[18:19], off
	global_load_dword v22, v[16:17], off
	v_mad_u64_u32 v[16:17], s[34:35], v20, s83, v[4:5]
	v_mad_u64_u32 v[18:19], s[34:35], v7, s83, v[4:5]
	s_add_i32 s18, s16, 20
	s_add_i32 s17, s14, 20
	v_or_b32_e32 v7, s17, v3
	v_or_b32_e32 v20, s18, v2
	s_waitcnt vmcnt(1)
	ds_write_b32 v16, v21
	s_waitcnt vmcnt(0)
	ds_write_b32 v18, v22
	s_sleep 8
	v_or_b32_e32 v18, s18, v10
	v_or_b32_e32 v16, s17, v5
	v_ashrrev_i32_e32 v19, 31, v18
	v_ashrrev_i32_e32 v17, 31, v16
	v_lshlrev_b64 v[18:19], 12, v[18:19]
	v_lshlrev_b64 v[16:17], 12, v[16:17]
	v_lshl_add_u64 v[18:19], v[8:9], 0, v[18:19]
	v_lshl_add_u64 v[16:17], v[8:9], 0, v[16:17]
	global_load_dword v21, v[18:19], off
	global_load_dword v22, v[16:17], off
	v_mad_u64_u32 v[16:17], s[34:35], v20, s83, v[4:5]
	v_mad_u64_u32 v[18:19], s[34:35], v7, s83, v[4:5]
	s_add_i32 s18, s16, 24
	s_add_i32 s17, s14, 24
	v_or_b32_e32 v7, s17, v3
	v_or_b32_e32 v20, s18, v2
	s_add_i32 s16, s16, 28
	s_add_i32 s14, s14, 28
	s_cmp_lg_u32 s11, 0
	s_waitcnt vmcnt(1)
	ds_write_b32 v16, v21
	s_waitcnt vmcnt(0)
	ds_write_b32 v18, v22
	s_sleep 8
	v_or_b32_e32 v18, s18, v10
	v_or_b32_e32 v16, s17, v5
	v_ashrrev_i32_e32 v19, 31, v18
	v_ashrrev_i32_e32 v17, 31, v16
	v_lshlrev_b64 v[18:19], 12, v[18:19]
	v_lshlrev_b64 v[16:17], 12, v[16:17]
	v_lshl_add_u64 v[18:19], v[8:9], 0, v[18:19]
	v_lshl_add_u64 v[16:17], v[8:9], 0, v[16:17]
	global_load_dword v21, v[18:19], off
	global_load_dword v22, v[16:17], off
	v_mad_u64_u32 v[16:17], s[34:35], v20, s83, v[4:5]
	v_mad_u64_u32 v[18:19], s[34:35], v7, s83, v[4:5]
	v_or_b32_e32 v20, s16, v2
	v_or_b32_e32 v7, s14, v3
	s_waitcnt vmcnt(1)
	ds_write_b32 v16, v21
	s_waitcnt vmcnt(0)
	ds_write_b32 v18, v22
	s_sleep 8
	v_or_b32_e32 v18, s16, v10
	v_or_b32_e32 v16, s14, v5
	v_ashrrev_i32_e32 v19, 31, v18
	v_ashrrev_i32_e32 v17, 31, v16
	v_lshlrev_b64 v[18:19], 12, v[18:19]
	v_lshlrev_b64 v[16:17], 12, v[16:17]
	v_lshl_add_u64 v[18:19], v[8:9], 0, v[18:19]
	v_lshl_add_u64 v[16:17], v[8:9], 0, v[16:17]
	global_load_dword v21, v[18:19], off
	global_load_dword v22, v[16:17], off
	v_mad_u64_u32 v[16:17], s[16:17], v20, s83, v[4:5]
	v_mad_u64_u32 v[18:19], s[16:17], v7, s83, v[4:5]
	s_waitcnt vmcnt(1)
	ds_write_b32 v16, v21
	s_waitcnt vmcnt(0)
	ds_write_b32 v18, v22
	s_sleep 8
	s_cbranch_scc1 .LBB0_152
; #define LAS __attribute__((address_space(3)))
; __device__ __forceinline__ unsigned pkbf(float lo, float hi) { f32x2 v = {lo, hi}; bf16x2v b = __builtin_convertvector(v, bf16x2v); return __builtin_bit_cast(unsigned, b); }
; template <int MODE> __device__ __forceinline__ void transpose_item(const float* W, int K, int N, bf16_t* WT, LAS float* scr, int item, int lane) {
;     ...
;     asm volatile("s_waitcnt lgkmcnt(0)" ::: "memory");
;     const int c = lane & 7;
; #pragma unroll
;     for (int j = 0; j < 4; ++j) {
;         const int n = (lane >> 3) + 8 * j, gn = n0 + n; const LAS float* s = scr + (8 * c) * 33 + n;
;         const int drow = MODE == 0 ? gn : (MODE == 1 ? (gn >= 8608 ? gn + 96 : gn) : (gn < DFF ? 2 * gn : 2 * (gn - DFF) + 1));
;         u32x4 o; o.x = pkbf(s[0 * 33], s[1 * 33]); o.y = pkbf(s[2 * 33], s[3 * 33]); o.z = pkbf(s[4 * 33], s[5 * 33]); o.w = pkbf(s[6 * 33], s[7 * 33]);
;         *(u32x4*)(WT + (size_t)drow * K + k0 + 8 * c) = o;
;     }
;     asm volatile("s_waitcnt lgkmcnt(0)" ::: "memory");
; __device__ __forceinline__ void ph_wconv(CArgs& a, int l, unsigned char* ldsg, int gw, int ngw, int lane, int wv, int mask) {
;     ...
;     if (mask & 2) for (int it = gw; it < 3 * I_SQ; it += ngw) { const int wh = it / I_SQ; transpose_item<0>(a.in[27 + wh] + (size_t)l * 1048576, 1024, 1024, (bf16_t*)(ws + WS_WA + (size_t)wh * 2 * MiB), scr, it % I_SQ, lane); }
	s_lshl_b64 s[10:11], s[42:43], 21
	s_add_u32 s7, s4, s10
	s_waitcnt lgkmcnt(0)
	s_addc_u32 s14, s5, s11
	s_ashr_i32 s45, s44, 31
	ds_read2_b32 v[22:23], v12 offset0:33 offset1:41
	ds_read2_b32 v[24:25], v12 offset1:8
	ds_read2_b32 v[26:27], v12 offset0:66 offset1:74
	ds_read2_b32 v[28:29], v12 offset0:99 offset1:107
	ds_read2_b32 v[30:31], v12 offset0:132 offset1:140
	ds_read2_b32 v[32:33], v12 offset0:165 offset1:173
	ds_read2_b32 v[34:35], v12 offset0:198 offset1:206
	ds_read2_b32 v[36:37], v12 offset0:231 offset1:239
	s_lshl_b64 s[10:11], s[44:45], 1
	s_add_u32 s10, s7, s10
	v_or_b32_e32 v20, s40, v11
	s_addc_u32 s11, s14, s11
	v_mov_b32_e32 v7, v1
	v_ashrrev_i32_e32 v21, 31, v20
	v_lshl_add_u64 v[8:9], s[10:11], 0, v[6:7]
	v_lshlrev_b64 v[20:21], 11, v[20:21]
	s_waitcnt lgkmcnt(6)
	v_cvt_pk_bf16_f32 v16, v24, v22
	s_waitcnt lgkmcnt(4)
	v_cvt_pk_bf16_f32 v17, v26, v28
	s_waitcnt lgkmcnt(2)
	v_cvt_pk_bf16_f32 v18, v30, v32
	s_waitcnt lgkmcnt(0)
	v_cvt_pk_bf16_f32 v19, v34, v36
	v_lshl_add_u64 v[20:21], v[8:9], 0, v[20:21]
	global_store_dwordx4 v[20:21], v[16:19], off
	v_or_b32_e32 v20, s40, v13
	v_ashrrev_i32_e32 v21, 31, v20
	v_lshlrev_b64 v[20:21], 11, v[20:21]
	v_cvt_pk_bf16_f32 v16, v25, v23
	v_cvt_pk_bf16_f32 v17, v27, v29
	v_cvt_pk_bf16_f32 v18, v31, v33
	v_cvt_pk_bf16_f32 v19, v35, v37
	v_lshl_add_u64 v[20:21], v[8:9], 0, v[20:21]
	global_store_dwordx4 v[20:21], v[16:19], off
	ds_read2_b32 v[22:23], v12 offset0:49 offset1:57
	ds_read2_b32 v[24:25], v12 offset0:16 offset1:24
	ds_read2_b32 v[26:27], v12 offset0:82 offset1:90
	ds_read2_b32 v[28:29], v12 offset0:115 offset1:123
	ds_read2_b32 v[30:31], v12 offset0:148 offset1:156
	ds_read2_b32 v[32:33], v12 offset0:181 offset1:189
	ds_read2_b32 v[34:35], v12 offset0:214 offset1:222
	ds_read2_b32 v[36:37], v12 offset0:247 offset1:255
	v_or_b32_e32 v20, s40, v14
	v_ashrrev_i32_e32 v21, 31, v20
	v_lshlrev_b64 v[20:21], 11, v[20:21]
	s_waitcnt lgkmcnt(6)
	v_cvt_pk_bf16_f32 v16, v24, v22
	s_waitcnt lgkmcnt(4)
	v_cvt_pk_bf16_f32 v17, v26, v28
	s_waitcnt lgkmcnt(2)
	v_cvt_pk_bf16_f32 v18, v30, v32
	s_waitcnt lgkmcnt(0)
	v_cvt_pk_bf16_f32 v19, v34, v36
	v_lshl_add_u64 v[20:21], v[8:9], 0, v[20:21]
	global_store_dwordx4 v[20:21], v[16:19], off
	v_or_b32_e32 v20, s40, v15
	v_ashrrev_i32_e32 v21, 31, v20
	v_lshlrev_b64 v[20:21], 11, v[20:21]
	v_cvt_pk_bf16_f32 v16, v25, v23
	v_cvt_pk_bf16_f32 v17, v27, v29
	v_cvt_pk_bf16_f32 v18, v31, v33
	v_cvt_pk_bf16_f32 v19, v35, v37
	v_lshl_add_u64 v[8:9], v[8:9], 0, v[20:21]
	global_store_dwordx4 v[8:9], v[16:19], off
	s_waitcnt lgkmcnt(0)
	s_add_i32 s6, s6, s80
	s_cmpk_gt_i32 s6, 0x5ff
	s_cbranch_scc0 .LBB0_151

; template <int MODE> __device__ __forceinline__ void transpose_item(const float* W, int K, int N, bf16_t* WT, LAS float* scr, int item, int lane) {
;     const int nblk = N / 32, kb = item / nblk, nb = item % nblk, k0 = 64 * kb, n0 = 32 * nb;
; #pragma unroll 8
;     for (int i = 0; i < 32; ++i) { const int kk = 2 * i + (lane >> 5); scr[kk * 33 + (lane & 31)] = W[(size_t)(k0 + kk) * N + n0 + (lane & 31)]; }
.LBB0_159:
	s_lshl_b32 s17, s11, 1
	s_lshl_b32 s16, s10, 1
	v_or_b32_e32 v18, s17, v10
	v_or_b32_e32 v16, s16, v5
	v_ashrrev_i32_e32 v19, 31, v18
	v_ashrrev_i32_e32 v17, 31, v16
	v_lshlrev_b64 v[18:19], 12, v[18:19]
	v_lshlrev_b64 v[16:17], 12, v[16:17]
	v_lshl_add_u64 v[18:19], v[8:9], 0, v[18:19]
	v_lshl_add_u64 v[16:17], v[8:9], 0, v[16:17]
	global_load_dword v21, v[18:19], off
	global_load_dword v22, v[16:17], off
	v_or_b32_e32 v7, s16, v3
	v_or_b32_e32 v20, s17, v2
	v_mad_u64_u32 v[16:17], s[34:35], v20, s83, v[4:5]
	v_mad_u64_u32 v[18:19], s[34:35], v7, s83, v[4:5]
	s_add_i32 s27, s17, 4
	s_add_i32 s18, s16, 4
	v_or_b32_e32 v7, s18, v3
	v_or_b32_e32 v20, s27, v2
	s_add_i32 s11, s11, 16
	s_add_i32 s10, s10, 16
	s_add_i32 s14, s14, -16
	s_waitcnt vmcnt(0)
	ds_write_b32 v16, v21
	s_sleep 8
	ds_write_b32 v18, v22
	v_or_b32_e32 v18, s27, v10
	v_or_b32_e32 v16, s18, v5
	v_ashrrev_i32_e32 v19, 31, v18
	v_ashrrev_i32_e32 v17, 31, v16
	v_lshlrev_b64 v[18:19], 12, v[18:19]
	v_lshlrev_b64 v[16:17], 12, v[16:17]
	v_lshl_add_u64 v[18:19], v[8:9], 0, v[18:19]
	v_lshl_add_u64 v[16:17], v[8:9], 0, v[16:17]
	global_load_dword v21, v[18:19], off
	global_load_dword v22, v[16:17], off
	v_mad_u64_u32 v[16:17], s[34:35], v20, s83, v[4:5]
	v_mad_u64_u32 v[18:19], s[34:35], v7, s83, v[4:5]
	s_add_i32 s27, s17, 8
	s_add_i32 s18, s16, 8
	v_or_b32_e32 v7, s18, v3
	v_or_b32_e32 v20, s27, v2
	s_waitcnt vmcnt(1)
	ds_write_b32 v16, v21
	s_waitcnt vmcnt(0)
	ds_write_b32 v18, v22
	s_sleep 8
	v_or_b32_e32 v18, s27, v10
	v_or_b32_e32 v16, s18, v5
	v_ashrrev_i32_e32 v19, 31, v18
	v_ashrrev_i32_e32 v17, 31, v16
	v_lshlrev_b64 v[18:19], 12, v[18:19]
	v_lshlrev_b64 v[16:17], 12, v[16:17]
	v_lshl_add_u64 v[18:19], v[8:9], 0, v[18:19]
	v_lshl_add_u64 v[16:17], v[8:9], 0, v[16:17]
	global_load_dword v21, v[18:19], off
	global_load_dword v22, v[16:17], off
	v_mad_u64_u32 v[16:17], s[34:35], v20, s83, v[4:5]
	v_mad_u64_u32 v[18:19], s[34:35], v7, s83, v[4:5]
	s_add_i32 s27, s17, 12
	s_add_i32 s18, s16, 12
	v_or_b32_e32 v7, s18, v3
	v_or_b32_e32 v20, s27, v2
	s_waitcnt vmcnt(1)
	ds_write_b32 v16, v21
	s_waitcnt vmcnt(0)
	ds_write_b32 v18, v22
	s_sleep 8
	v_or_b32_e32 v18, s27, v10
	v_or_b32_e32 v16, s18, v5
	v_ashrrev_i32_e32 v19, 31, v18
	v_ashrrev_i32_e32 v17, 31, v16
	v_lshlrev_b64 v[18:19], 12, v[18:19]
	v_lshlrev_b64 v[16:17], 12, v[16:17]
	v_lshl_add_u64 v[18:19], v[8:9], 0, v[18:19]
	v_lshl_add_u64 v[16:17], v[8:9], 0, v[16:17]
	global_load_dword v21, v[18:19], off
	global_load_dword v22, v[16:17], off
	v_mad_u64_u32 v[16:17], s[34:35], v20, s83, v[4:5]
	v_mad_u64_u32 v[18:19], s[34:35], v7, s83, v[4:5]
	s_add_i32 s27, s17, 16
	s_add_i32 s18, s16, 16
	v_or_b32_e32 v7, s18, v3
	v_or_b32_e32 v20, s27, v2
	s_waitcnt vmcnt(1)
	ds_write_b32 v16, v21
	s_waitcnt vmcnt(0)
	ds_write_b32 v18, v22
	s_sleep 8
	v_or_b32_e32 v18, s27, v10
	v_or_b32_e32 v16, s18, v5
	v_ashrrev_i32_e32 v19, 31, v18
	v_ashrrev_i32_e32 v17, 31, v16
	v_lshlrev_b64 v[18:19], 12, v[18:19]
	v_lshlrev_b64 v[16:17], 12, v[16:17]
	v_lshl_add_u64 v[18:19], v[8:9], 0, v[18:19]
	v_lshl_add_u64 v[16:17], v[8:9], 0, v[16:17]
	global_load_dword v21, v[18:19], off
	global_load_dword v22, v[16:17], off
	v_mad_u64_u32 v[16:17], s[34:35], v20, s83, v[4:5]
	v_mad_u64_u32 v[18:19], s[34:35], v7, s83, v[4:5]
	s_add_i32 s27, s17, 20
	s_add_i32 s18, s16, 20
	v_or_b32_e32 v7, s18, v3
	v_or_b32_e32 v20, s27, v2
	s_waitcnt vmcnt(1)
	ds_write_b32 v16, v21
	s_waitcnt vmcnt(0)
	ds_write_b32 v18, v22
	s_sleep 8
	v_or_b32_e32 v18, s27, v10
	v_or_b32_e32 v16, s18, v5
	v_ashrrev_i32_e32 v19, 31, v18
	v_ashrrev_i32_e32 v17, 31, v16
	v_lshlrev_b64 v[18:19], 12, v[18:19]
	v_lshlrev_b64 v[16:17], 12, v[16:17]
	v_lshl_add_u64 v[18:19], v[8:9], 0, v[18:19]
	v_lshl_add_u64 v[16:17], v[8:9], 0, v[16:17]
	global_load_dword v21, v[18:19], off
	global_load_dword v22, v[16:17], off
	v_mad_u64_u32 v[16:17], s[34:35], v20, s83, v[4:5]
	v_mad_u64_u32 v[18:19], s[34:35], v7, s83, v[4:5]
	s_add_i32 s27, s17, 24
	s_add_i32 s18, s16, 24
	v_or_b32_e32 v7, s18, v3
	v_or_b32_e32 v20, s27, v2
	s_add_i32 s17, s17, 28
	s_add_i32 s16, s16, 28
	s_cmp_lg_u32 s14, 0
	s_waitcnt vmcnt(1)
	ds_write_b32 v16, v21
	s_waitcnt vmcnt(0)
	ds_write_b32 v18, v22
	s_sleep 8
	v_or_b32_e32 v18, s27, v10
	v_or_b32_e32 v16, s18, v5
	v_ashrrev_i32_e32 v19, 31, v18
	v_ashrrev_i32_e32 v17, 31, v16
	v_lshlrev_b64 v[18:19], 12, v[18:19]
	v_lshlrev_b64 v[16:17], 12, v[16:17]
	v_lshl_add_u64 v[18:19], v[8:9], 0, v[18:19]
	v_lshl_add_u64 v[16:17], v[8:9], 0, v[16:17]
	global_load_dword v21, v[18:19], off
	global_load_dword v22, v[16:17], off
	v_mad_u64_u32 v[16:17], s[34:35], v20, s83, v[4:5]
	v_mad_u64_u32 v[18:19], s[34:35], v7, s83, v[4:5]
	v_or_b32_e32 v20, s17, v2
	v_or_b32_e32 v7, s16, v3
	s_waitcnt vmcnt(1)
	ds_write_b32 v16, v21
	s_waitcnt vmcnt(0)
	ds_write_b32 v18, v22
	s_sleep 8
	v_or_b32_e32 v18, s17, v10
	v_or_b32_e32 v16, s16, v5
	v_ashrrev_i32_e32 v19, 31, v18
	v_ashrrev_i32_e32 v17, 31, v16
	v_lshlrev_b64 v[18:19], 12, v[18:19]
	v_lshlrev_b64 v[16:17], 12, v[16:17]
	v_lshl_add_u64 v[18:19], v[8:9], 0, v[18:19]
	v_lshl_add_u64 v[16:17], v[8:9], 0, v[16:17]
	global_load_dword v21, v[18:19], off
	global_load_dword v22, v[16:17], off
	v_mad_u64_u32 v[16:17], s[16:17], v20, s83, v[4:5]
	v_mad_u64_u32 v[18:19], s[16:17], v7, s83, v[4:5]
	s_waitcnt vmcnt(1)
	ds_write_b32 v16, v21
	s_waitcnt vmcnt(0)
	ds_write_b32 v18, v22
	s_sleep 8
	s_cbranch_scc1 .LBB0_159
; #define LAS __attribute__((address_space(3)))
; __device__ __forceinline__ unsigned pkbf(float lo, float hi) { f32x2 v = {lo, hi}; bf16x2v b = __builtin_convertvector(v, bf16x2v); return __builtin_bit_cast(unsigned, b); }
; template <int MODE> __device__ __forceinline__ void transpose_item(const float* W, int K, int N, bf16_t* WT, LAS float* scr, int item, int lane) {
;     ...
;     asm volatile("s_waitcnt lgkmcnt(0)" ::: "memory");
;     const int c = lane & 7;
; #pragma unroll
;     for (int j = 0; j < 4; ++j) {
;         const int n = (lane >> 3) + 8 * j, gn = n0 + n; const LAS float* s = scr + (8 * c) * 33 + n;
;         const int drow = MODE == 0 ? gn : (MODE == 1 ? (gn >= 8608 ? gn + 96 : gn) : (gn < DFF ? 2 * gn : 2 * (gn - DFF) + 1));
;         u32x4 o; o.x = pkbf(s[0 * 33], s[1 * 33]); o.y = pkbf(s[2 * 33], s[3 * 33]); o.z = pkbf(s[4 * 33], s[5 * 33]); o.w = pkbf(s[6 * 33], s[7 * 33]);
;         *(u32x4*)(WT + (size_t)drow * K + k0 + 8 * c) = o;
;     }
;     asm volatile("s_waitcnt lgkmcnt(0)" ::: "memory");
; __device__ __forceinline__ void ph_wconv(CArgs& a, int l, unsigned char* ldsg, int gw, int ngw, int lane, int wv, int mask) {
;     ...
;     if (mask & 2) for (int it = gw; it < 3 * I_SQ; it += ngw) { const int wh = it / I_SQ; transpose_item<0>(a.in[27 + wh] + (size_t)l * 1048576, 1024, 1024, (bf16_t*)(ws + WS_WA + (size_t)wh * 2 * MiB), scr, it % I_SQ, lane); }
	s_lshl_b64 s[10:11], s[42:43], 21
	s_add_u32 s14, s6, s10
	s_waitcnt lgkmcnt(0)
	s_addc_u32 s16, s7, s11
	s_ashr_i32 s45, s44, 31
	ds_read2_b32 v[22:23], v12 offset0:33 offset1:41
	ds_read2_b32 v[24:25], v12 offset1:8
	ds_read2_b32 v[26:27], v12 offset0:66 offset1:74
	ds_read2_b32 v[28:29], v12 offset0:99 offset1:107
	ds_read2_b32 v[30:31], v12 offset0:132 offset1:140
	ds_read2_b32 v[32:33], v12 offset0:165 offset1:173
	ds_read2_b32 v[34:35], v12 offset0:198 offset1:206
	ds_read2_b32 v[36:37], v12 offset0:231 offset1:239
	s_lshl_b64 s[10:11], s[44:45], 1
	s_add_u32 s10, s14, s10
	v_or_b32_e32 v20, s40, v11
	s_addc_u32 s11, s16, s11
	v_mov_b32_e32 v7, v1
	v_ashrrev_i32_e32 v21, 31, v20
	v_lshl_add_u64 v[8:9], s[10:11], 0, v[6:7]
	v_lshlrev_b64 v[20:21], 11, v[20:21]
	s_waitcnt lgkmcnt(6)
	v_cvt_pk_bf16_f32 v16, v24, v22
	s_waitcnt lgkmcnt(4)
	v_cvt_pk_bf16_f32 v17, v26, v28
	s_waitcnt lgkmcnt(2)
	v_cvt_pk_bf16_f32 v18, v30, v32
	s_waitcnt lgkmcnt(0)
	v_cvt_pk_bf16_f32 v19, v34, v36
	v_lshl_add_u64 v[20:21], v[8:9], 0, v[20:21]
	global_store_dwordx4 v[20:21], v[16:19], off
	v_or_b32_e32 v20, s40, v13
	v_ashrrev_i32_e32 v21, 31, v20
	v_lshlrev_b64 v[20:21], 11, v[20:21]
	v_cvt_pk_bf16_f32 v16, v25, v23
	v_cvt_pk_bf16_f32 v17, v27, v29
	v_cvt_pk_bf16_f32 v18, v31, v33
	v_cvt_pk_bf16_f32 v19, v35, v37
	v_lshl_add_u64 v[20:21], v[8:9], 0, v[20:21]
	global_store_dwordx4 v[20:21], v[16:19], off
	ds_read2_b32 v[22:23], v12 offset0:49 offset1:57
	ds_read2_b32 v[24:25], v12 offset0:16 offset1:24
	ds_read2_b32 v[26:27], v12 offset0:82 offset1:90
	ds_read2_b32 v[28:29], v12 offset0:115 offset1:123
	ds_read2_b32 v[30:31], v12 offset0:148 offset1:156
	ds_read2_b32 v[32:33], v12 offset0:181 offset1:189
	ds_read2_b32 v[34:35], v12 offset0:214 offset1:222
	ds_read2_b32 v[36:37], v12 offset0:247 offset1:255
	v_or_b32_e32 v20, s40, v14
	v_ashrrev_i32_e32 v21, 31, v20
	v_lshlrev_b64 v[20:21], 11, v[20:21]
	s_waitcnt lgkmcnt(6)
	v_cvt_pk_bf16_f32 v16, v24, v22
	s_waitcnt lgkmcnt(4)
	v_cvt_pk_bf16_f32 v17, v26, v28
	s_waitcnt lgkmcnt(2)
	v_cvt_pk_bf16_f32 v18, v30, v32
	s_waitcnt lgkmcnt(0)
	v_cvt_pk_bf16_f32 v19, v34, v36
	v_lshl_add_u64 v[20:21], v[8:9], 0, v[20:21]
	global_store_dwordx4 v[20:21], v[16:19], off
	v_or_b32_e32 v20, s40, v15
	v_ashrrev_i32_e32 v21, 31, v20
	v_lshlrev_b64 v[20:21], 11, v[20:21]
	v_cvt_pk_bf16_f32 v16, v25, v23
	v_cvt_pk_bf16_f32 v17, v27, v29
	v_cvt_pk_bf16_f32 v18, v31, v33
	v_cvt_pk_bf16_f32 v19, v35, v37
	v_lshl_add_u64 v[8:9], v[8:9], 0, v[20:21]
	global_store_dwordx4 v[8:9], v[16:19], off
	s_waitcnt lgkmcnt(0)
	s_add_i32 s1, s3, s1
	s_cmpk_gt_i32 s1, 0x5ff
	s_cbranch_scc0 .LBB0_158
